# attention masks for the always-masked blocks from constant lane masks (scalar moves feed the selects; compare path kept for sequence-start jobs): 16 VALU per masked block instead of 32
# baseline (speedup 1.0000x reference)
; __device__ __forceinline__ void att_block(const bf16x8 (&kf)[4], const bf16x8 (&qf)[4], const bf16x8 (&va)[4], f32x16& o0, f32x16& o1, float& mrun, float& lrun, bool domask, int lo_, int hi_) {
;     ...
; #pragma unroll
;     for (int i = 0; i < 16; ++i) st[i] = 0.f;
; #pragma unroll
;     for (int kk = 0; kk < 4; ++kk) st = __builtin_amdgcn_mfma_f32_32x32x16_bf16(kf[kk], qf[kk], st, 0, 0, 0);
;     if (domask) {
;         asm volatile("" : "+v"(lo_), "+v"(hi_));
; #pragma unroll
;         for (int i = 0; i < 16; ++i) { const int ci = (i & 3) + 8 * (i >> 2); st[i] = ((ci - lo_) | (hi_ - ci)) < 0 ? -INFINITY : st[i]; }
;     }
;     float bmax = -INFINITY;
; #pragma unroll
;     for (int i = 0; i < 16; ++i) bmax = fmaxf(bmax, st[i]);
;     bmax = fmaxf(bmax, __shfl_xor(bmax, 32));
;     const float mnew = fmaxf(mrun, bmax);
;     float lsum = 0.f;
; #pragma unroll
;     for (int i = 0; i < 16; ++i) { st[i] = __builtin_amdgcn_exp2f(st[i] - mnew); lsum += st[i]; }
;     lsum += __shfl_xor(lsum, 32);
;     const float alpha = __builtin_amdgcn_exp2f(mrun - mnew);
;     lrun = lrun * alpha + lsum; mrun = mnew;
; #pragma unroll
;     for (int i = 0; i < 16; ++i) { o0[i] *= alpha; o1[i] *= alpha; }
; #pragma unroll
;     for (int s = 0; s < 2; ++s) { v4u w; w.x = pk2(st[8 * s], st[8 * s + 1]); w.y = pk2(st[8 * s + 2], st[8 * s + 3]); w.z = pk2(st[8 * s + 4], st[8 * s + 5]); w.w = pk2(st[8 * s + 6], st[8 * s + 7]);
;         const bf16x8 pb = __builtin_bit_cast(bf16x8, w);
;         o0 = __builtin_amdgcn_mfma_f32_32x32x16_bf16(va[2 * s], pb, o0, 0, 0, 0);
;         o1 = __builtin_amdgcn_mfma_f32_32x32x16_bf16(va[2 * s + 1], pb, o1, 0, 0, 0); }
; __device__ __forceinline__ void att_phase(unsigned char* ws, LAS unsigned char* lds, int lane, int wave, int G) {
;     ...
;             asm volatile("s_waitcnt vmcnt(0)" ::: "memory");
;             if (kb < 5) ATT_DMA_KV(P, kb + 1, sb ^ 1);
;             else if (hn) ATT_DMA_KV(N, 0, sb ^ 1);
;             bf16x8 kf[4], va[4];
; #pragma unroll
;             for (int kk = 0; kk < 4; ++kk) kf[kk] = *(LAS const bf16x8*)(kfb + sb * 4096 + (((2 * kk + h) ^ (qc & 7)) << 4));
;             LAS const unsigned char* trs = trb + 8192 + sb * 4096;
; #pragma unroll
;             for (int s = 0; s < 2; ++s) {
;                 const s16x4 lo0 = vtr(trs + (16 * s) * VP), hi0 = vtr(trs + (16 * s + 8) * VP);
.LBB0_80:
	v_add_u32_e32 v0, 0xffffffa0, v191
	v_mul_lo_u32 v0, s56, v0
	v_add_u32_e32 v4, s11, v0
	v_max_i32_e32 v164, 0, v4
	s_add_i32 s57, s33, 0x1000
	s_lshl_b32 s6, s56, 3
	s_waitcnt vmcnt(0)
	v_lshl_add_u32 v2, v164, 7, v180
	s_mov_b32 m0, s57
	s_add_i32 s7, s33, 0x3000
	v_add_u32_e32 v4, s6, v4
	global_load_lds_dwordx4 v2, s[98:99]
	v_lshl_add_u32 v0, v164, 7, v182
	s_mov_b32 m0, s7
	v_max_i32_e32 v164, 0, v4
	global_load_lds_dwordx4 v0, s[100:101]
	v_readlane_b32 s15, v254, 28
	v_lshl_add_u32 v2, v164, 7, v180
	s_mov_b32 m0, s15
	v_readlane_b32 s15, v254, 29
	v_add_u32_e32 v4, s6, v4
	global_load_lds_dwordx4 v2, s[98:99]
	v_lshl_add_u32 v0, v164, 7, v182
	s_mov_b32 m0, s15
	v_max_i32_e32 v164, 0, v4
	global_load_lds_dwordx4 v0, s[100:101]
	s_add_i32 s15, s33, 0x1800
	v_lshl_add_u32 v2, v164, 7, v180
	s_mov_b32 m0, s15
	s_add_i32 s17, s33, 0x3800
	v_add_u32_e32 v51, s6, v4
	global_load_lds_dwordx4 v2, s[98:99]
	v_lshl_add_u32 v0, v164, 7, v182
	s_mov_b32 m0, s17
	v_max_i32_e32 v164, 0, v51
	global_load_lds_dwordx4 v0, s[100:101]
	s_add_i32 s21, s33, 0x1c00
	v_lshl_add_u32 v2, v164, 7, v180
	s_mov_b32 m0, s21
	v_readlane_b32 s59, v254, 30
	global_load_lds_dwordx4 v2, s[98:99]
	v_lshl_add_u32 v0, v164, 7, v182
	s_mov_b32 m0, s59
	v_max_i32_e32 v199, s58, v189
	global_load_lds_dwordx4 v0, s[100:101]
	ds_read_b128 v[0:3], v225
	ds_read_b128 v[16:19], v226
	s_waitcnt vmcnt(0) lgkmcnt(0)
	v_mfma_f32_32x32x16_bf16 v[0:15], v[0:3], v[128:131], 0
	ds_read_b128 v[20:23], v228
	s_mov_b32 s59, 0xff800000
	v_mfma_f32_32x32x16_bf16 v[0:15], v[16:19], v[124:127], v[0:15]
	ds_read_b128 v[16:19], v227
	ds_read_b64_tr_b16 v[34:35], v229 offset:8192
	ds_read_b64_tr_b16 v[36:37], v229 offset:9216
	ds_read_b64_tr_b16 v[40:41], v229 offset:9280
	ds_read_b64_tr_b16 v[38:39], v229 offset:8256
	ds_read_b64_tr_b16 v[42:43], v229 offset:10240
	ds_read_b64_tr_b16 v[44:45], v229 offset:11264
	ds_read_b64_tr_b16 v[48:49], v229 offset:11328
	ds_read_b64_tr_b16 v[46:47], v229 offset:10304
	s_waitcnt lgkmcnt(8)
	v_mfma_f32_32x32x16_bf16 v[0:15], v[16:19], v[120:123], v[0:15]
	v_sub_u32_e32 v16, v199, v193
	v_mov_b32_e32 v17, v214
	s_waitcnt lgkmcnt(0)
	s_nop 0
	v_mfma_f32_32x32x16_bf16 v[0:15], v[20:23], v[116:119], v[0:15]
	s_nop 6
	s_cmp_lg_u32 s58, 0
	s_cbranch_scc1 .Lmk_slow_0
	s_mov_b32 vcc_lo, 0x1
	s_mov_b32 vcc_hi, 0x1f
	s_mov_b32 s24, 0x3
	s_mov_b32 s25, 0x3f
	s_mov_b32 s26, 0x7
	s_mov_b32 s27, 0x7f
	s_mov_b32 s28, 0xf
	s_mov_b32 s29, 0xff
	s_nop 0
	v_cndmask_b32_e32 v0, v211, v0, vcc
	s_mov_b32 vcc_lo, 0x1ff
	s_mov_b32 vcc_hi, 0x1fff
	v_cndmask_b32_e64 v1, v211, v1, s[24:25]
	s_mov_b32 s24, 0x3ff
	s_mov_b32 s25, 0x3fff
	v_cndmask_b32_e64 v2, v211, v2, s[26:27]
	s_mov_b32 s26, 0x7ff
	s_mov_b32 s27, 0x7fff
	v_cndmask_b32_e64 v3, v211, v3, s[28:29]
	s_mov_b32 s28, 0xfff
	s_mov_b32 s29, 0xffff
	v_cndmask_b32_e32 v4, v211, v4, vcc
	s_mov_b32 vcc_lo, 0x1ffff
	s_mov_b32 vcc_hi, 0x1fffff
	v_cndmask_b32_e64 v5, v211, v5, s[24:25]
	s_mov_b32 s24, 0x3ffff
	s_mov_b32 s25, 0x3fffff
	v_cndmask_b32_e64 v6, v211, v6, s[26:27]
	s_mov_b32 s26, 0x7ffff
	s_mov_b32 s27, 0x7fffff
	v_cndmask_b32_e64 v7, v211, v7, s[28:29]
	s_mov_b32 s28, 0xfffff
	s_mov_b32 s29, 0xffffff
	v_cndmask_b32_e32 v8, v211, v8, vcc
	s_mov_b32 vcc_lo, 0x1ffffff
	s_mov_b32 vcc_hi, 0x1fffffff
	v_cndmask_b32_e64 v9, v211, v9, s[24:25]
	s_mov_b32 s24, 0x3ffffff
	s_mov_b32 s25, 0x3fffffff
	v_cndmask_b32_e64 v10, v211, v10, s[26:27]
	s_mov_b32 s26, 0x7ffffff
	s_mov_b32 s27, 0x7fffffff
	v_cndmask_b32_e64 v11, v211, v11, s[28:29]
	s_mov_b32 s28, 0xfffffff
	s_mov_b32 s29, 0xffffffff
	v_cndmask_b32_e32 v56, v211, v12, vcc
	v_cndmask_b32_e64 v57, v211, v13, s[24:25]
	v_cndmask_b32_e64 v58, v211, v14, s[26:27]
	v_cndmask_b32_e64 v59, v211, v15, s[28:29]
	s_branch .Lmk_done_0
.Lmk_slow_0:
	v_cmp_ge_i32_e32 vcc, 0, v16
	v_cmp_ge_i32_e64 s[24:25], 1, v16
	v_cmp_ge_i32_e64 s[26:27], 2, v16
	v_cmp_ge_i32_e64 s[28:29], 3, v16
	s_nop 0
	v_cndmask_b32_e32 v0, v211, v0, vcc
	v_cmp_ge_i32_e32 vcc, 8, v16
	v_cndmask_b32_e64 v1, v211, v1, s[24:25]
	v_cmp_ge_i32_e64 s[24:25], 9, v16
	v_cndmask_b32_e64 v2, v211, v2, s[26:27]
	v_cmp_ge_i32_e64 s[26:27], 10, v16
	v_cndmask_b32_e64 v3, v211, v3, s[28:29]
	v_cmp_ge_i32_e64 s[28:29], 11, v16
	v_cndmask_b32_e32 v4, v211, v4, vcc
	v_cmp_ge_i32_e32 vcc, 16, v16
	v_cndmask_b32_e64 v5, v211, v5, s[24:25]
	v_cmp_ge_i32_e64 s[24:25], 17, v16
	v_cndmask_b32_e64 v6, v211, v6, s[26:27]
	v_cmp_ge_i32_e64 s[26:27], 18, v16
	v_cndmask_b32_e64 v7, v211, v7, s[28:29]
	v_cmp_ge_i32_e64 s[28:29], 19, v16
	v_cndmask_b32_e32 v8, v211, v8, vcc
	v_cmp_ge_i32_e32 vcc, 24, v16
	v_cndmask_b32_e64 v9, v211, v9, s[24:25]
	v_cmp_ge_i32_e64 s[24:25], 25, v16
	v_cndmask_b32_e64 v10, v211, v10, s[26:27]
	v_cmp_ge_i32_e64 s[26:27], 26, v16
	v_cndmask_b32_e64 v11, v211, v11, s[28:29]
	v_cmp_ge_i32_e64 s[28:29], 27, v16
	v_cndmask_b32_e32 v56, v211, v12, vcc
	v_cndmask_b32_e64 v57, v211, v13, s[24:25]
	v_cndmask_b32_e64 v58, v211, v14, s[26:27]
	v_cndmask_b32_e64 v59, v211, v15, s[28:29]
; __device__ __forceinline__ void att_block(const bf16x8 (&kf)[4], const bf16x8 (&qf)[4], const bf16x8 (&va)[4], f32x16& o0, f32x16& o1, float& mrun, float& lrun, bool domask, int lo_, int hi_) {
;     ...
; #pragma unroll
;     for (int i = 0; i < 16; ++i) st[i] = 0.f;
; #pragma unroll
;     for (int kk = 0; kk < 4; ++kk) st = __builtin_amdgcn_mfma_f32_32x32x16_bf16(kf[kk], qf[kk], st, 0, 0, 0);
;     if (domask) {
;         asm volatile("" : "+v"(lo_), "+v"(hi_));
; #pragma unroll
;         for (int i = 0; i < 16; ++i) { const int ci = (i & 3) + 8 * (i >> 2); st[i] = ((ci - lo_) | (hi_ - ci)) < 0 ? -INFINITY : st[i]; }
;     }
;     float bmax = -INFINITY;
; #pragma unroll
;     for (int i = 0; i < 16; ++i) bmax = fmaxf(bmax, st[i]);
;     bmax = fmaxf(bmax, __shfl_xor(bmax, 32));
;     const float mnew = fmaxf(mrun, bmax);
;     float lsum = 0.f;
; #pragma unroll
;     for (int i = 0; i < 16; ++i) { st[i] = __builtin_amdgcn_exp2f(st[i] - mnew); lsum += st[i]; }
;     lsum += __shfl_xor(lsum, 32);
;     const float alpha = __builtin_amdgcn_exp2f(mrun - mnew);
;     lrun = lrun * alpha + lsum; mrun = mnew;
; #pragma unroll
;     for (int i = 0; i < 16; ++i) { o0[i] *= alpha; o1[i] *= alpha; }
; #pragma unroll
;     for (int s = 0; s < 2; ++s) { v4u w; w.x = pk2(st[8 * s], st[8 * s + 1]); w.y = pk2(st[8 * s + 2], st[8 * s + 3]); w.z = pk2(st[8 * s + 4], st[8 * s + 5]); w.w = pk2(st[8 * s + 6], st[8 * s + 7]);
;         const bf16x8 pb = __builtin_bit_cast(bf16x8, w);
;         o0 = __builtin_amdgcn_mfma_f32_32x32x16_bf16(va[2 * s], pb, o0, 0, 0, 0);
;         o1 = __builtin_amdgcn_mfma_f32_32x32x16_bf16(va[2 * s + 1], pb, o1, 0, 0, 0); }
; __device__ __forceinline__ void att_phase(unsigned char* ws, LAS unsigned char* lds, int lane, int wave, int G) {
;     ...
;             asm volatile("s_waitcnt vmcnt(0)" ::: "memory");
;             if (kb < 5) ATT_DMA_KV(P, kb + 1, sb ^ 1);
;             else if (hn) ATT_DMA_KV(N, 0, sb ^ 1);
;             bf16x8 kf[4], va[4];
; #pragma unroll
;             for (int kk = 0; kk < 4; ++kk) kf[kk] = *(LAS const bf16x8*)(kfb + sb * 4096 + (((2 * kk + h) ^ (qc & 7)) << 4));
;             LAS const unsigned char* trs = trb + 8192 + sb * 4096;
; #pragma unroll
;             for (int s = 0; s < 2; ++s) {
;                 const s16x4 lo0 = vtr(trs + (16 * s) * VP), hi0 = vtr(trs + (16 * s + 8) * VP);
.Lmk_done_0:
	s_nop 0
	s_nop 0
	v_max3_f32 v12, v0, s59, v1
	v_max3_f32 v12, v12, v2, v3
	v_max3_f32 v12, v12, v4, v5
	v_max3_f32 v12, v12, v6, v7
	v_max3_f32 v12, v12, v8, v9
	v_xor_b32_e32 v13, 32, v206
	v_max3_f32 v12, v12, v10, v11
	v_cmp_lt_i32_e32 vcc, v13, v208
	v_max3_f32 v12, v12, v56, v57
	v_max3_f32 v12, v12, v58, v59
	v_cndmask_b32_e32 v13, v206, v13, vcc
	v_lshlrev_b32_e32 v201, 2, v13
	ds_bpermute_b32 v13, v201, v12
	s_mov_b32 s59, 0xf149f2ca
	s_waitcnt lgkmcnt(0)
	v_max3_f32 v50, v12, v13, s59
	v_sub_f32_e32 v0, v0, v50
	v_exp_f32_e32 v16, v0
	v_sub_f32_e32 v0, v1, v50
	v_exp_f32_e32 v17, v0
	v_sub_f32_e32 v1, v2, v50
	v_exp_f32_e32 v18, v1
	v_sub_f32_e32 v1, v3, v50
	v_exp_f32_e32 v19, v1
	v_sub_f32_e32 v1, v4, v50
	v_add_f32_e32 v0, 0, v16
	v_exp_f32_e32 v20, v1
	v_sub_f32_e32 v1, v5, v50
	v_add_f32_e32 v0, v17, v0
	v_exp_f32_e32 v21, v1
	v_sub_f32_e32 v1, v6, v50
	v_add_f32_e32 v0, v18, v0
	v_exp_f32_e32 v22, v1
	v_sub_f32_e32 v1, v7, v50
	v_add_f32_e32 v0, v19, v0
	v_exp_f32_e32 v23, v1
	v_sub_f32_e32 v1, v8, v50
	v_add_f32_e32 v0, v20, v0
	v_exp_f32_e32 v60, v1
	v_sub_f32_e32 v1, v9, v50
	v_add_f32_e32 v0, v21, v0
	v_exp_f32_e32 v61, v1
	v_add_f32_e32 v0, v22, v0
	v_add_f32_e32 v0, v23, v0
	v_add_f32_e32 v0, v60, v0
	v_add_f32_e32 v62, v61, v0
	v_sub_f32_e32 v1, v10, v50
	v_cvt_pk_bf16_f32 v52, v16, v17
	v_sub_f32_e32 v16, v56, v50
	v_mov_b32_e32 v0, 0
	v_exp_f32_e32 v63, v1
	v_sub_f32_e32 v64, v11, v50
	v_cvt_pk_bf16_f32 v53, v18, v19
	v_cvt_pk_bf16_f32 v54, v20, v21
	v_cvt_pk_bf16_f32 v55, v22, v23
	v_exp_f32_e32 v56, v16
	v_sub_f32_e32 v16, v57, v50
	v_mfma_f32_32x32x16_bf16 v[18:33], v[34:37], v[52:55], 0
	v_exp_f32_e32 v57, v16
	v_sub_f32_e32 v34, v58, v50
	v_exp_f32_e32 v64, v64
	v_cvt_pk_bf16_f32 v36, v56, v57
	s_nop 1
	v_exp_f32_e32 v1, v34
	v_sub_f32_e32 v34, v59, v50
	v_mfma_f32_32x32x16_bf16 v[2:17], v[38:41], v[52:55], 0
	v_exp_f32_e32 v38, v34
	v_add_f32_e32 v39, v63, v62
	v_add_f32_e32 v39, v64, v39
	v_cvt_pk_bf16_f32 v34, v60, v61
	v_cvt_pk_bf16_f32 v35, v63, v64
	v_cvt_pk_bf16_f32 v37, v1, v38
	v_add_f32_e32 v39, v56, v39
	v_add_f32_e32 v39, v57, v39
	v_mfma_f32_32x32x16_bf16 v[18:33], v[42:45], v[34:37], v[18:33]
	v_add_f32_e32 v1, v1, v39
	v_add_f32_e32 v1, v38, v1
	ds_bpermute_b32 v232, v201, v1
	v_mfma_f32_32x32x16_bf16 v[2:17], v[46:49], v[34:37], v[2:17]
	v_add_u32_e32 v38, s6, v51
	v_max_i32_e32 v164, 0, v38
	s_mov_b32 m0, s33
	s_waitcnt vmcnt(0)
	v_lshl_add_u32 v36, v164, 7, v180
	v_add_u32_e32 v38, s6, v38
	global_load_lds_dwordx4 v36, s[98:99]
	v_lshl_add_u32 v34, v164, 7, v182
	s_mov_b32 m0, s44
	v_max_i32_e32 v164, 0, v38
	global_load_lds_dwordx4 v34, s[100:101]
	v_lshl_add_u32 v36, v164, 7, v180
	s_mov_b32 m0, s66
	v_add_u32_e32 v38, s6, v38
	global_load_lds_dwordx4 v36, s[98:99]
	v_lshl_add_u32 v34, v164, 7, v182
	s_mov_b32 m0, s67
	v_max_i32_e32 v164, 0, v38
	global_load_lds_dwordx4 v34, s[100:101]
	v_lshl_add_u32 v36, v164, 7, v180
	s_mov_b32 m0, s48
	v_lshl_add_u32 v34, v164, 7, v182
	global_load_lds_dwordx4 v36, s[98:99]
	s_mov_b32 m0, s49
	v_readlane_b32 s59, v254, 27
	global_load_lds_dwordx4 v34, s[100:101]
	v_add_u32_e32 v34, s6, v38
	v_max_i32_e32 v164, 0, v34
	v_lshl_add_u32 v36, v164, 7, v180
	s_mov_b32 m0, s72
	v_lshl_add_u32 v34, v164, 7, v182
	global_load_lds_dwordx4 v36, s[98:99]
	s_mov_b32 m0, s59
	s_cmp_gt_i32 s58, 32
	global_load_lds_dwordx4 v34, s[100:101]
	ds_read_b128 v[68:71], v225 offset:4096
	ds_read_b128 v[64:67], v226 offset:4096
	s_waitcnt lgkmcnt(0)
	v_mfma_f32_32x32x16_bf16 v[34:49], v[68:71], v[128:131], 0
	ds_read_b128 v[60:63], v227 offset:4096
	ds_read_b128 v[56:59], v228 offset:4096
	s_waitcnt vmcnt(0)
	ds_read_b64_tr_b16 v[52:53], v229 offset:12288
	ds_read_b64_tr_b16 v[54:55], v229 offset:13312
	ds_read_b64_tr_b16 v[94:95], v229 offset:13376
	ds_read_b64_tr_b16 v[92:93], v229 offset:12352
	ds_read_b64_tr_b16 v[88:89], v229 offset:14336
	ds_read_b64_tr_b16 v[90:91], v229 offset:15360
	ds_read_b64_tr_b16 v[86:87], v229 offset:15424
	ds_read_b64_tr_b16 v[84:85], v229 offset:14400
	v_mfma_f32_32x32x16_bf16 v[34:49], v[64:67], v[124:127], v[34:49]
	s_waitcnt lgkmcnt(9)
	v_mfma_f32_32x32x16_bf16 v[34:49], v[60:63], v[120:123], v[34:49]
	s_waitcnt lgkmcnt(8)
	v_mfma_f32_32x32x16_bf16 v[34:49], v[56:59], v[116:119], v[34:49]
	s_cbranch_scc0 .LBB0_82
	v_sub_u32_e32 v51, v199, v215
	v_mov_b32_e32 v72, v216
	s_nop 0
	s_nop 1
	v_cmp_ge_i32_e32 vcc, 0, v51
	v_cmp_ge_i32_e64 s[24:25], 1, v51
	v_cmp_ge_i32_e64 s[26:27], 2, v51
	v_cmp_ge_i32_e64 s[28:29], 3, v51
	s_nop 1
	v_cndmask_b32_e32 v34, v211, v34, vcc
	v_cmp_ge_i32_e32 vcc, 8, v51
	v_cndmask_b32_e64 v35, v211, v35, s[24:25]
	v_cmp_ge_i32_e64 s[24:25], 9, v51
	v_cndmask_b32_e64 v36, v211, v36, s[26:27]
	v_cmp_ge_i32_e64 s[26:27], 10, v51
	v_cndmask_b32_e64 v37, v211, v37, s[28:29]
	v_cmp_ge_i32_e64 s[28:29], 11, v51
	v_cndmask_b32_e32 v38, v211, v38, vcc
	v_cmp_ge_i32_e32 vcc, 16, v51
	v_cndmask_b32_e64 v39, v211, v39, s[24:25]
	v_cmp_ge_i32_e64 s[24:25], 17, v51
	v_cndmask_b32_e64 v40, v211, v40, s[26:27]
	v_cmp_ge_i32_e64 s[26:27], 18, v51
	v_cndmask_b32_e64 v41, v211, v41, s[28:29]
	v_cmp_ge_i32_e64 s[28:29], 19, v51
	v_cndmask_b32_e32 v42, v211, v42, vcc
	v_cmp_ge_i32_e32 vcc, 24, v51
	v_cndmask_b32_e64 v43, v211, v43, s[24:25]
	v_cmp_ge_i32_e64 s[24:25], 25, v51
	v_cndmask_b32_e64 v44, v211, v44, s[26:27]
	v_cmp_ge_i32_e64 s[26:27], 26, v51
	v_cndmask_b32_e64 v45, v211, v45, s[28:29]
	v_cmp_ge_i32_e64 s[28:29], 27, v51
	v_cndmask_b32_e32 v46, v211, v46, vcc
	v_cndmask_b32_e64 v47, v211, v47, s[24:25]
	v_cndmask_b32_e64 v48, v211, v48, s[26:27]
	v_cndmask_b32_e64 v49, v211, v49, s[28:29]
	s_nop 0
	s_nop 1
; __device__ __forceinline__ unsigned pk2(float lo, float hi) { return pg8::cvt_pk_bf16(lo, hi); }
; __device__ __forceinline__ void att_block(const bf16x8 (&kf)[4], const bf16x8 (&qf)[4], const bf16x8 (&va)[4], f32x16& o0, f32x16& o1, float& mrun, float& lrun, bool domask, int lo_, int hi_) {
;     ...
; #pragma unroll
;     for (int i = 0; i < 16; ++i) st[i] = 0.f;
; #pragma unroll
;     for (int kk = 0; kk < 4; ++kk) st = __builtin_amdgcn_mfma_f32_32x32x16_bf16(kf[kk], qf[kk], st, 0, 0, 0);
;     if (domask) {
;         asm volatile("" : "+v"(lo_), "+v"(hi_));
; #pragma unroll
;         for (int i = 0; i < 16; ++i) { const int ci = (i & 3) + 8 * (i >> 2); st[i] = ((ci - lo_) | (hi_ - ci)) < 0 ? -INFINITY : st[i]; }
;     }
;     float bmax = -INFINITY;
; #pragma unroll
;     for (int i = 0; i < 16; ++i) bmax = fmaxf(bmax, st[i]);
;     bmax = fmaxf(bmax, __shfl_xor(bmax, 32));
;     const float mnew = fmaxf(mrun, bmax);
;     float lsum = 0.f;
; #pragma unroll
;     for (int i = 0; i < 16; ++i) { st[i] = __builtin_amdgcn_exp2f(st[i] - mnew); lsum += st[i]; }
;     lsum += __shfl_xor(lsum, 32);
;     const float alpha = __builtin_amdgcn_exp2f(mrun - mnew);
;     lrun = lrun * alpha + lsum; mrun = mnew;
; #pragma unroll
;     for (int i = 0; i < 16; ++i) { o0[i] *= alpha; o1[i] *= alpha; }
; #pragma unroll
;     for (int s = 0; s < 2; ++s) { v4u w; w.x = pk2(st[8 * s], st[8 * s + 1]); w.y = pk2(st[8 * s + 2], st[8 * s + 3]); w.z = pk2(st[8 * s + 4], st[8 * s + 5]); w.w = pk2(st[8 * s + 6], st[8 * s + 7]);
;         const bf16x8 pb = __builtin_bit_cast(bf16x8, w);
;         o0 = __builtin_amdgcn_mfma_f32_32x32x16_bf16(va[2 * s], pb, o0, 0, 0, 0);
;         o1 = __builtin_amdgcn_mfma_f32_32x32x16_bf16(va[2 * s + 1], pb, o1, 0, 0, 0); }
; __device__ __forceinline__ void att_phase(unsigned char* ws, LAS unsigned char* lds, int lane, int wave, int G) {
;     ...
;             if (kb >= 1) {
;                 att_block(kf, qfB, va, oB0, oB1, mB, lB, kb == 1 || kb == 5 || kminB > 32 * (kb - 1), mloB - 4 * h - 32 * (kb - 1), qc + 128 - 4 * h - 32 * (kb - 1));
.LBB0_82:
	s_mov_b32 s59, 0xff800000
	s_nop 9
	v_max3_f32 v51, v34, s59, v35
	v_max3_f32 v51, v51, v36, v37
	v_max3_f32 v51, v51, v38, v39
	v_max3_f32 v51, v51, v40, v41
	v_max3_f32 v51, v51, v42, v43
	v_max3_f32 v51, v51, v44, v45
	v_max3_f32 v51, v51, v46, v47
	v_max3_f32 v51, v51, v48, v49
	ds_bpermute_b32 v72, v201, v51
	v_max_i32_e32 v237, s14, v189
	s_mov_b32 s60, 0xff800000
	s_waitcnt lgkmcnt(0)
	v_max3_f32 v148, v50, v51, v72
	v_sub_f32_e32 v34, v34, v148
	v_exp_f32_e32 v72, v34
	v_sub_f32_e32 v35, v35, v148
	v_exp_f32_e32 v73, v35
	v_sub_f32_e32 v35, v36, v148
	v_exp_f32_e32 v74, v35
	v_sub_f32_e32 v35, v37, v148
	v_exp_f32_e32 v75, v35
	v_sub_f32_e32 v35, v38, v148
	v_add_f32_e32 v34, 0, v72
	v_exp_f32_e32 v76, v35
	v_sub_f32_e32 v35, v39, v148
	v_add_f32_e32 v34, v73, v34
	v_exp_f32_e32 v77, v35
	v_sub_f32_e32 v35, v40, v148
	v_add_f32_e32 v34, v74, v34
	v_exp_f32_e32 v78, v35
	v_sub_f32_e32 v35, v41, v148
	v_add_f32_e32 v34, v75, v34
	v_exp_f32_e32 v79, v35
	v_sub_f32_e32 v35, v42, v148
	v_add_f32_e32 v34, v76, v34
	v_exp_f32_e32 v80, v35
	v_sub_f32_e32 v35, v43, v148
	v_add_f32_e32 v34, v77, v34
	v_exp_f32_e32 v81, v35
	v_sub_f32_e32 v35, v44, v148
	v_add_f32_e32 v34, v78, v34
	v_exp_f32_e32 v82, v35
	v_sub_f32_e32 v35, v45, v148
	v_add_f32_e32 v34, v79, v34
	v_exp_f32_e32 v83, v35
	v_sub_f32_e32 v35, v46, v148
	v_add_f32_e32 v34, v80, v34
	v_exp_f32_e32 v96, v35
	v_sub_f32_e32 v35, v47, v148
	v_add_f32_e32 v34, v81, v34
	v_exp_f32_e32 v97, v35
	v_sub_f32_e32 v35, v48, v148
	v_add_f32_e32 v34, v82, v34
	v_exp_f32_e32 v98, v35
	v_sub_f32_e32 v35, v49, v148
	v_add_f32_e32 v34, v83, v34
	v_exp_f32_e32 v99, v35
	v_add_f32_e32 v34, v96, v34
	v_add_f32_e32 v34, v97, v34
	v_add_f32_e32 v34, v98, v34
	v_add_f32_e32 v235, v99, v34
	v_sub_f32_e32 v34, v50, v148
	v_exp_f32_e32 v188, v34
	ds_bpermute_b32 v236, v201, v235
	v_pk_mul_f32 v[34:35], v[32:33], v[188:189] op_sel_hi:[1,0]
	v_pk_mul_f32 v[32:33], v[30:31], v[188:189] op_sel_hi:[1,0]
	v_pk_mul_f32 v[30:31], v[28:29], v[188:189] op_sel_hi:[1,0]
	v_pk_mul_f32 v[28:29], v[26:27], v[188:189] op_sel_hi:[1,0]
	v_pk_mul_f32 v[26:27], v[24:25], v[188:189] op_sel_hi:[1,0]
	v_pk_mul_f32 v[24:25], v[22:23], v[188:189] op_sel_hi:[1,0]
	v_pk_mul_f32 v[22:23], v[20:21], v[188:189] op_sel_hi:[1,0]
	v_pk_mul_f32 v[20:21], v[18:19], v[188:189] op_sel_hi:[1,0]
	v_pk_mul_f32 v[50:51], v[16:17], v[188:189] op_sel_hi:[1,0]
	v_pk_mul_f32 v[48:49], v[14:15], v[188:189] op_sel_hi:[1,0]
	v_pk_mul_f32 v[46:47], v[12:13], v[188:189] op_sel_hi:[1,0]
	v_pk_mul_f32 v[44:45], v[10:11], v[188:189] op_sel_hi:[1,0]
	v_pk_mul_f32 v[42:43], v[8:9], v[188:189] op_sel_hi:[1,0]
	v_pk_mul_f32 v[40:41], v[6:7], v[188:189] op_sel_hi:[1,0]
	v_pk_mul_f32 v[38:39], v[4:5], v[188:189] op_sel_hi:[1,0]
	v_pk_mul_f32 v[36:37], v[2:3], v[188:189] op_sel_hi:[1,0]
	v_cvt_pk_bf16_f32 v2, v72, v73
	v_cvt_pk_bf16_f32 v3, v74, v75
	v_cvt_pk_bf16_f32 v4, v76, v77
	v_cvt_pk_bf16_f32 v5, v78, v79
	v_sub_u32_e32 v18, v237, v193
	v_mov_b32_e32 v19, v214
	v_mfma_f32_32x32x16_bf16 v[20:35], v[52:55], v[2:5], v[20:35]
	s_waitcnt lgkmcnt(0)
	v_mfma_f32_32x32x16_bf16 v[36:51], v[92:95], v[2:5], v[36:51]
	v_cvt_pk_bf16_f32 v2, v80, v81
	v_cvt_pk_bf16_f32 v3, v82, v83
	v_cvt_pk_bf16_f32 v4, v96, v97
	v_cvt_pk_bf16_f32 v5, v98, v99
	s_nop 1
	v_mfma_f32_32x32x16_bf16 v[20:35], v[88:91], v[2:5], v[20:35]
	v_mfma_f32_32x32x16_bf16 v[36:51], v[84:87], v[2:5], v[36:51]
	v_mfma_f32_32x32x16_bf16 v[2:17], v[68:71], v[112:115], 0
	v_mfma_f32_32x32x16_bf16 v[2:17], v[64:67], v[108:111], v[2:17]
	v_mfma_f32_32x32x16_bf16 v[2:17], v[60:63], v[104:107], v[2:17]
	v_mfma_f32_32x32x16_bf16 v[2:17], v[56:59], v[100:103], v[2:17]
	s_nop 4
	s_cmp_lg_u32 s14, 0
	s_cbranch_scc1 .Lmk_slow_2
	s_mov_b32 vcc_lo, 0x1
	s_mov_b32 vcc_hi, 0x1f
	s_mov_b32 s24, 0x3
	s_mov_b32 s25, 0x3f
	s_mov_b32 s26, 0x7
	s_mov_b32 s27, 0x7f
	s_mov_b32 s28, 0xf
	s_mov_b32 s29, 0xff
	s_nop 2
	v_cndmask_b32_e32 v2, v211, v2, vcc
	s_mov_b32 vcc_lo, 0x1ff
	s_mov_b32 vcc_hi, 0x1fff
	v_cndmask_b32_e64 v3, v211, v3, s[24:25]
	s_mov_b32 s24, 0x3ff
	s_mov_b32 s25, 0x3fff
	v_cndmask_b32_e64 v4, v211, v4, s[26:27]
	s_mov_b32 s26, 0x7ff
	s_mov_b32 s27, 0x7fff
	v_cndmask_b32_e64 v5, v211, v5, s[28:29]
	s_mov_b32 s28, 0xfff
	s_mov_b32 s29, 0xffff
	v_cndmask_b32_e32 v6, v211, v6, vcc
	s_mov_b32 vcc_lo, 0x1ffff
	s_mov_b32 vcc_hi, 0x1fffff
	v_cndmask_b32_e64 v7, v211, v7, s[24:25]
	s_mov_b32 s24, 0x3ffff
	s_mov_b32 s25, 0x3fffff
	v_cndmask_b32_e64 v8, v211, v8, s[26:27]
	s_mov_b32 s26, 0x7ffff
	s_mov_b32 s27, 0x7fffff
	v_cndmask_b32_e64 v9, v211, v9, s[28:29]
	s_mov_b32 s28, 0xfffff
	s_mov_b32 s29, 0xffffff
	v_cndmask_b32_e32 v10, v211, v10, vcc
	s_mov_b32 vcc_lo, 0x1ffffff
	s_mov_b32 vcc_hi, 0x1fffffff
	v_cndmask_b32_e64 v11, v211, v11, s[24:25]
	s_mov_b32 s24, 0x3ffffff
	s_mov_b32 s25, 0x3fffffff
	v_cndmask_b32_e64 v12, v211, v12, s[26:27]
	s_mov_b32 s26, 0x7ffffff
	s_mov_b32 s27, 0x7fffffff
	v_cndmask_b32_e64 v13, v211, v13, s[28:29]
	s_mov_b32 s28, 0xfffffff
	s_mov_b32 s29, 0xffffffff
	v_cndmask_b32_e32 v14, v211, v14, vcc
	v_cndmask_b32_e64 v15, v211, v15, s[24:25]
	v_cndmask_b32_e64 v16, v211, v16, s[26:27]
	v_cndmask_b32_e64 v17, v211, v17, s[28:29]
	s_branch .Lmk_done_2
; __device__ __forceinline__ void att_block(const bf16x8 (&kf)[4], const bf16x8 (&qf)[4], const bf16x8 (&va)[4], f32x16& o0, f32x16& o1, float& mrun, float& lrun, bool domask, int lo_, int hi_) {
;     ...
; #pragma unroll
;     for (int i = 0; i < 16; ++i) st[i] = 0.f;
; #pragma unroll
;     for (int kk = 0; kk < 4; ++kk) st = __builtin_amdgcn_mfma_f32_32x32x16_bf16(kf[kk], qf[kk], st, 0, 0, 0);
;     if (domask) {
;         asm volatile("" : "+v"(lo_), "+v"(hi_));
; #pragma unroll
;         for (int i = 0; i < 16; ++i) { const int ci = (i & 3) + 8 * (i >> 2); st[i] = ((ci - lo_) | (hi_ - ci)) < 0 ? -INFINITY : st[i]; }
;     }
;     float bmax = -INFINITY;
; #pragma unroll
;     for (int i = 0; i < 16; ++i) bmax = fmaxf(bmax, st[i]);
;     bmax = fmaxf(bmax, __shfl_xor(bmax, 32));
;     const float mnew = fmaxf(mrun, bmax);
;     float lsum = 0.f;
; #pragma unroll
;     for (int i = 0; i < 16; ++i) { st[i] = __builtin_amdgcn_exp2f(st[i] - mnew); lsum += st[i]; }
;     lsum += __shfl_xor(lsum, 32);
;     const float alpha = __builtin_amdgcn_exp2f(mrun - mnew);
;     lrun = lrun * alpha + lsum; mrun = mnew;
; #pragma unroll
;     for (int i = 0; i < 16; ++i) { o0[i] *= alpha; o1[i] *= alpha; }
; #pragma unroll
;     for (int s = 0; s < 2; ++s) { v4u w; w.x = pk2(st[8 * s], st[8 * s + 1]); w.y = pk2(st[8 * s + 2], st[8 * s + 3]); w.z = pk2(st[8 * s + 4], st[8 * s + 5]); w.w = pk2(st[8 * s + 6], st[8 * s + 7]);
;         const bf16x8 pb = __builtin_bit_cast(bf16x8, w);
;         o0 = __builtin_amdgcn_mfma_f32_32x32x16_bf16(va[2 * s], pb, o0, 0, 0, 0);
;         o1 = __builtin_amdgcn_mfma_f32_32x32x16_bf16(va[2 * s + 1], pb, o1, 0, 0, 0); }
; __device__ __forceinline__ void att_phase(unsigned char* ws, LAS unsigned char* lds, int lane, int wave, int G) {
;     ...
;             asm volatile("s_waitcnt vmcnt(0)" ::: "memory");
;             if (kb < 5) ATT_DMA_KV(P, kb + 1, sb ^ 1);
;             else if (hn) ATT_DMA_KV(N, 0, sb ^ 1);
;             bf16x8 kf[4], va[4];
; #pragma unroll
;             for (int kk = 0; kk < 4; ++kk) kf[kk] = *(LAS const bf16x8*)(kfb + sb * 4096 + (((2 * kk + h) ^ (qc & 7)) << 4));
;             LAS const unsigned char* trs = trb + 8192 + sb * 4096;
; #pragma unroll
;             for (int s = 0; s < 2; ++s) {
;                 const s16x4 lo0 = vtr(trs + (16 * s) * VP), hi0 = vtr(trs + (16 * s + 8) * VP);
.Lmk_slow_2:
	v_cmp_ge_i32_e32 vcc, 0, v18
	v_cmp_ge_i32_e64 s[24:25], 1, v18
	v_cmp_ge_i32_e64 s[26:27], 2, v18
	v_cmp_ge_i32_e64 s[28:29], 3, v18
	s_nop 2
	v_cndmask_b32_e32 v2, v211, v2, vcc
	v_cmp_ge_i32_e32 vcc, 8, v18
	v_cndmask_b32_e64 v3, v211, v3, s[24:25]
	v_cmp_ge_i32_e64 s[24:25], 9, v18
	v_cndmask_b32_e64 v4, v211, v4, s[26:27]
	v_cmp_ge_i32_e64 s[26:27], 10, v18
	v_cndmask_b32_e64 v5, v211, v5, s[28:29]
	v_cmp_ge_i32_e64 s[28:29], 11, v18
	v_cndmask_b32_e32 v6, v211, v6, vcc
	v_cmp_ge_i32_e32 vcc, 16, v18
	v_cndmask_b32_e64 v7, v211, v7, s[24:25]
	v_cmp_ge_i32_e64 s[24:25], 17, v18
	v_cndmask_b32_e64 v8, v211, v8, s[26:27]
	v_cmp_ge_i32_e64 s[26:27], 18, v18
	v_cndmask_b32_e64 v9, v211, v9, s[28:29]
	v_cmp_ge_i32_e64 s[28:29], 19, v18
	v_cndmask_b32_e32 v10, v211, v10, vcc
	v_cmp_ge_i32_e32 vcc, 24, v18
	v_cndmask_b32_e64 v11, v211, v11, s[24:25]
	v_cmp_ge_i32_e64 s[24:25], 25, v18
	v_cndmask_b32_e64 v12, v211, v12, s[26:27]
	v_cmp_ge_i32_e64 s[26:27], 26, v18
	v_cndmask_b32_e64 v13, v211, v13, s[28:29]
	v_cmp_ge_i32_e64 s[28:29], 27, v18
	v_cndmask_b32_e32 v14, v211, v14, vcc
	v_cndmask_b32_e64 v15, v211, v15, s[24:25]
	v_cndmask_b32_e64 v16, v211, v16, s[26:27]
	v_cndmask_b32_e64 v17, v211, v17, s[28:29]
.Lmk_done_2:
	s_nop 0
	v_max3_f32 v18, v2, s59, v3
	v_max3_f32 v18, v18, v4, v5
	v_max3_f32 v18, v18, v6, v7
	v_max3_f32 v18, v18, v8, v9
	v_max3_f32 v18, v18, v10, v11
	v_max3_f32 v18, v18, v12, v13
	v_max3_f32 v18, v18, v14, v15
	v_max3_f32 v18, v18, v16, v17
	ds_bpermute_b32 v19, v201, v18
	s_mov_b32 s59, 0xf149f2ca
	s_waitcnt lgkmcnt(0)
	v_max3_f32 v150, v18, v19, s59
	v_sub_f32_e32 v2, v2, v150
	v_exp_f32_e32 v18, v2
	v_sub_f32_e32 v3, v3, v150
	v_exp_f32_e32 v19, v3
	v_sub_f32_e32 v3, v4, v150
	v_exp_f32_e32 v56, v3
	v_sub_f32_e32 v3, v5, v150
	v_exp_f32_e32 v57, v3
	v_sub_f32_e32 v3, v6, v150
	v_add_f32_e32 v2, 0, v18
	v_exp_f32_e32 v58, v3
	v_sub_f32_e32 v3, v7, v150
	v_add_f32_e32 v2, v19, v2
	v_exp_f32_e32 v59, v3
	v_sub_f32_e32 v3, v8, v150
	v_add_f32_e32 v2, v56, v2
	v_exp_f32_e32 v60, v3
	v_sub_f32_e32 v3, v9, v150
	v_add_f32_e32 v2, v57, v2
	v_exp_f32_e32 v61, v3
	v_sub_f32_e32 v3, v10, v150
	v_add_f32_e32 v2, v58, v2
	v_exp_f32_e32 v132, v3
	v_sub_f32_e32 v3, v11, v150
	v_add_f32_e32 v2, v59, v2
	v_exp_f32_e32 v133, v3
	v_sub_f32_e32 v3, v12, v150
	v_add_f32_e32 v2, v60, v2
	v_exp_f32_e32 v134, v3
	v_sub_f32_e32 v3, v13, v150
	v_add_f32_e32 v2, v61, v2
	v_exp_f32_e32 v135, v3
	v_sub_f32_e32 v3, v14, v150
	v_add_f32_e32 v2, v132, v2
	v_exp_f32_e32 v136, v3
	v_sub_f32_e32 v3, v15, v150
	v_add_f32_e32 v2, v133, v2
	v_exp_f32_e32 v137, v3
	v_sub_f32_e32 v3, v16, v150
	v_add_f32_e32 v2, v134, v2
	v_exp_f32_e32 v138, v3
	v_sub_f32_e32 v3, v17, v150
	v_add_f32_e32 v2, v135, v2
	v_exp_f32_e32 v139, v3
	v_add_f32_e32 v2, v136, v2
	v_add_f32_e32 v2, v137, v2
	v_add_f32_e32 v2, v138, v2
	v_add_f32_e32 v233, v139, v2
	v_cvt_pk_bf16_f32 v96, v18, v19
	v_cvt_pk_bf16_f32 v97, v56, v57
	v_cvt_pk_bf16_f32 v98, v58, v59
	v_mov_b32_e32 v2, 0
	v_cvt_pk_bf16_f32 v99, v60, v61
	ds_bpermute_b32 v234, v201, v233
	s_nop 0
	v_mfma_f32_32x32x16_bf16 v[68:83], v[52:55], v[96:99], 0
	v_cvt_pk_bf16_f32 v4, v132, v133
	v_cvt_pk_bf16_f32 v5, v134, v135
	v_mfma_f32_32x32x16_bf16 v[52:67], v[92:95], v[96:99], 0
	v_cvt_pk_bf16_f32 v6, v136, v137
	v_cvt_pk_bf16_f32 v7, v138, v139
	s_nop 1
	v_mfma_f32_32x32x16_bf16 v[68:83], v[88:91], v[4:7], v[68:83]
	v_mfma_f32_32x32x16_bf16 v[52:67], v[84:87], v[4:7], v[52:67]
	v_mul_lo_u32 v3, s56, v217
	v_add_u32_e32 v3, s11, v3
	v_max_i32_e32 v164, 0, v3
	s_mov_b32 m0, s57
	s_waitcnt vmcnt(0)
	v_lshl_add_u32 v6, v164, 7, v180
	v_add_u32_e32 v3, s6, v3
	global_load_lds_dwordx4 v6, s[98:99]
	v_lshl_add_u32 v4, v164, 7, v182
	s_mov_b32 m0, s7
	v_max_i32_e32 v164, 0, v3
	global_load_lds_dwordx4 v4, s[100:101]
	v_readlane_b32 s59, v254, 28
	v_lshl_add_u32 v6, v164, 7, v180
	s_mov_b32 m0, s59
	v_readlane_b32 s59, v254, 29
	v_add_u32_e32 v3, s6, v3
	global_load_lds_dwordx4 v6, s[98:99]
	v_lshl_add_u32 v4, v164, 7, v182
	s_mov_b32 m0, s59
	v_max_i32_e32 v164, 0, v3
	global_load_lds_dwordx4 v4, s[100:101]
	v_lshl_add_u32 v6, v164, 7, v180
	s_mov_b32 m0, s15
	v_add_u32_e32 v3, s6, v3
	global_load_lds_dwordx4 v6, s[98:99]
	v_lshl_add_u32 v4, v164, 7, v182
	s_mov_b32 m0, s17
	v_max_i32_e32 v164, 0, v3
	global_load_lds_dwordx4 v4, s[100:101]
	v_lshl_add_u32 v6, v164, 7, v180
	s_mov_b32 m0, s21
	v_readlane_b32 s59, v254, 30
	global_load_lds_dwordx4 v6, s[98:99]
	v_lshl_add_u32 v4, v164, 7, v182
	s_mov_b32 m0, s59
	s_cmpk_lt_i32 s58, 0x41
	global_load_lds_dwordx4 v4, s[100:101]
	ds_read_b128 v[144:147], v225
	ds_read_b128 v[140:143], v226
	s_waitcnt lgkmcnt(0)
	v_mfma_f32_32x32x16_bf16 v[4:19], v[144:147], v[128:131], 0
	ds_read_b128 v[136:139], v227
	ds_read_b128 v[132:135], v228
	s_waitcnt vmcnt(0)
	ds_read_b64_tr_b16 v[96:97], v229 offset:8192
	ds_read_b64_tr_b16 v[98:99], v229 offset:9216
	ds_read_b64_tr_b16 v[94:95], v229 offset:9280
	ds_read_b64_tr_b16 v[92:93], v229 offset:8256
	ds_read_b64_tr_b16 v[88:89], v229 offset:10240
	ds_read_b64_tr_b16 v[90:91], v229 offset:11264
	ds_read_b64_tr_b16 v[86:87], v229 offset:11328
	ds_read_b64_tr_b16 v[84:85], v229 offset:10304
	v_mfma_f32_32x32x16_bf16 v[4:19], v[140:143], v[124:127], v[4:19]
	s_waitcnt lgkmcnt(9)
	v_mfma_f32_32x32x16_bf16 v[4:19], v[136:139], v[120:123], v[4:19]
	s_waitcnt lgkmcnt(8)
	v_mfma_f32_32x32x16_bf16 v[4:19], v[132:135], v[116:119], v[4:19]
	s_cbranch_scc1 .LBB0_84
	v_sub_u32_e32 v3, v199, v218
	v_mov_b32_e32 v149, v219
	s_nop 0
	s_nop 1
	v_cmp_ge_i32_e32 vcc, 0, v3
	v_cmp_ge_i32_e64 s[24:25], 1, v3
	v_cmp_ge_i32_e64 s[26:27], 2, v3
	v_cmp_ge_i32_e64 s[28:29], 3, v3
	s_nop 1
	v_cndmask_b32_e32 v4, v211, v4, vcc
	v_cmp_ge_i32_e32 vcc, 8, v3
	v_cndmask_b32_e64 v5, v211, v5, s[24:25]
	v_cmp_ge_i32_e64 s[24:25], 9, v3
	v_cndmask_b32_e64 v6, v211, v6, s[26:27]
	v_cmp_ge_i32_e64 s[26:27], 10, v3
	v_cndmask_b32_e64 v7, v211, v7, s[28:29]
	v_cmp_ge_i32_e64 s[28:29], 11, v3
	v_cndmask_b32_e32 v8, v211, v8, vcc
	v_cmp_ge_i32_e32 vcc, 16, v3
	v_cndmask_b32_e64 v9, v211, v9, s[24:25]
	v_cmp_ge_i32_e64 s[24:25], 17, v3
	v_cndmask_b32_e64 v10, v211, v10, s[26:27]
	v_cmp_ge_i32_e64 s[26:27], 18, v3
	v_cndmask_b32_e64 v11, v211, v11, s[28:29]
	v_cmp_ge_i32_e64 s[28:29], 19, v3
	v_cndmask_b32_e32 v12, v211, v12, vcc
	v_cmp_ge_i32_e32 vcc, 24, v3
	v_cndmask_b32_e64 v13, v211, v13, s[24:25]
	v_cmp_ge_i32_e64 s[24:25], 25, v3
	v_cndmask_b32_e64 v14, v211, v14, s[26:27]
	v_cmp_ge_i32_e64 s[26:27], 26, v3
	v_cndmask_b32_e64 v15, v211, v15, s[28:29]
	v_cmp_ge_i32_e64 s[28:29], 27, v3
	v_cndmask_b32_e32 v16, v211, v16, vcc
	v_cndmask_b32_e64 v17, v211, v17, s[24:25]
	v_cndmask_b32_e64 v18, v211, v18, s[26:27]
	v_cndmask_b32_e64 v19, v211, v19, s[28:29]
	s_nop 0
	s_nop 1

; __device__ __forceinline__ void att_block(const bf16x8 (&kf)[4], const bf16x8 (&qf)[4], const bf16x8 (&va)[4], f32x16& o0, f32x16& o1, float& mrun, float& lrun, bool domask, int lo_, int hi_) {
;     ...
; #pragma unroll
;     for (int i = 0; i < 16; ++i) st[i] = 0.f;
; #pragma unroll
;     for (int kk = 0; kk < 4; ++kk) st = __builtin_amdgcn_mfma_f32_32x32x16_bf16(kf[kk], qf[kk], st, 0, 0, 0);
;     if (domask) {
;         asm volatile("" : "+v"(lo_), "+v"(hi_));
; #pragma unroll
;         for (int i = 0; i < 16; ++i) { const int ci = (i & 3) + 8 * (i >> 2); st[i] = ((ci - lo_) | (hi_ - ci)) < 0 ? -INFINITY : st[i]; }
;     }
;     float bmax = -INFINITY;
; #pragma unroll
;     for (int i = 0; i < 16; ++i) bmax = fmaxf(bmax, st[i]);
;     bmax = fmaxf(bmax, __shfl_xor(bmax, 32));
;     const float mnew = fmaxf(mrun, bmax);
;     float lsum = 0.f;
; #pragma unroll
;     for (int i = 0; i < 16; ++i) { st[i] = __builtin_amdgcn_exp2f(st[i] - mnew); lsum += st[i]; }
;     lsum += __shfl_xor(lsum, 32);
;     const float alpha = __builtin_amdgcn_exp2f(mrun - mnew);
;     lrun = lrun * alpha + lsum; mrun = mnew;
; #pragma unroll
;     for (int i = 0; i < 16; ++i) { o0[i] *= alpha; o1[i] *= alpha; }
; #pragma unroll
;     for (int s = 0; s < 2; ++s) { v4u w; w.x = pk2(st[8 * s], st[8 * s + 1]); w.y = pk2(st[8 * s + 2], st[8 * s + 3]); w.z = pk2(st[8 * s + 4], st[8 * s + 5]); w.w = pk2(st[8 * s + 6], st[8 * s + 7]);
;         const bf16x8 pb = __builtin_bit_cast(bf16x8, w);
;         o0 = __builtin_amdgcn_mfma_f32_32x32x16_bf16(va[2 * s], pb, o0, 0, 0, 0);
;         o1 = __builtin_amdgcn_mfma_f32_32x32x16_bf16(va[2 * s + 1], pb, o1, 0, 0, 0); }
; __device__ __forceinline__ void att_phase(unsigned char* ws, LAS unsigned char* lds, int lane, int wave, int G) {
;     ...
;             asm volatile("s_waitcnt vmcnt(0)" ::: "memory");
;             if (kb < 5) ATT_DMA_KV(P, kb + 1, sb ^ 1);
;             else if (hn) ATT_DMA_KV(N, 0, sb ^ 1);
;             bf16x8 kf[4], va[4];
; #pragma unroll
;             for (int kk = 0; kk < 4; ++kk) kf[kk] = *(LAS const bf16x8*)(kfb + sb * 4096 + (((2 * kk + h) ^ (qc & 7)) << 4));
;             LAS const unsigned char* trs = trb + 8192 + sb * 4096;
; #pragma unroll
;             for (int s = 0; s < 2; ++s) {
;                 const s16x4 lo0 = vtr(trs + (16 * s) * VP), hi0 = vtr(trs + (16 * s + 8) * VP);
.LBB0_90:
	v_mul_lo_u32 v84, s52, v189
	s_mov_b32 s58, 0xff800000
	v_add_u32_e32 v198, s53, v84
	s_nop 7
	v_max3_f32 v84, v68, s58, v69
	v_max3_f32 v84, v84, v70, v71
	v_max3_f32 v84, v84, v72, v73
	v_max3_f32 v84, v84, v74, v75
	v_max3_f32 v84, v84, v76, v77
	v_max3_f32 v84, v84, v78, v79
	v_max3_f32 v84, v84, v80, v81
	v_max3_f32 v84, v84, v82, v83
	ds_bpermute_b32 v85, v201, v84
	s_waitcnt lgkmcnt(0)
	s_waitcnt lgkmcnt(0)
	v_max3_f32 v245, v148, v84, v85
	v_sub_f32_e32 v68, v68, v245
	v_exp_f32_e32 v149, v68
	v_sub_f32_e32 v69, v69, v245
	v_exp_f32_e32 v150, v69
	v_sub_f32_e32 v69, v70, v245
	v_exp_f32_e32 v151, v69
	v_sub_f32_e32 v69, v71, v245
	v_exp_f32_e32 v152, v69
	v_sub_f32_e32 v69, v72, v245
	v_add_f32_e32 v68, 0, v149
	v_exp_f32_e32 v153, v69
	v_sub_f32_e32 v69, v73, v245
	v_add_f32_e32 v68, v150, v68
	v_exp_f32_e32 v154, v69
	v_sub_f32_e32 v69, v74, v245
	v_add_f32_e32 v68, v151, v68
	v_exp_f32_e32 v155, v69
	v_sub_f32_e32 v69, v75, v245
	v_add_f32_e32 v68, v152, v68
	v_exp_f32_e32 v156, v69
	v_sub_f32_e32 v69, v76, v245
	v_add_f32_e32 v68, v153, v68
	v_exp_f32_e32 v157, v69
	v_sub_f32_e32 v69, v77, v245
	v_add_f32_e32 v68, v154, v68
	v_exp_f32_e32 v158, v69
	v_sub_f32_e32 v69, v78, v245
	v_add_f32_e32 v68, v155, v68
	v_exp_f32_e32 v159, v69
	v_sub_f32_e32 v69, v79, v245
	v_add_f32_e32 v68, v156, v68
	v_exp_f32_e32 v160, v69
	v_sub_f32_e32 v69, v80, v245
	v_add_f32_e32 v68, v157, v68
	v_exp_f32_e32 v161, v69
	v_sub_f32_e32 v69, v81, v245
	v_add_f32_e32 v68, v158, v68
	v_exp_f32_e32 v162, v69
	v_sub_f32_e32 v69, v82, v245
	v_add_f32_e32 v68, v159, v68
	v_exp_f32_e32 v163, v69
	v_sub_f32_e32 v69, v83, v245
	v_add_f32_e32 v68, v160, v68
	v_exp_f32_e32 v164, v69
	v_add_f32_e32 v68, v161, v68
	v_add_f32_e32 v68, v162, v68
	v_add_f32_e32 v68, v163, v68
	v_add_f32_e32 v241, v164, v68
	v_sub_f32_e32 v68, v148, v245
	v_exp_f32_e32 v194, v68
	ds_bpermute_b32 v242, v201, v241
	v_pk_mul_f32 v[82:83], v[50:51], v[194:195] op_sel_hi:[1,0]
	v_pk_mul_f32 v[80:81], v[48:49], v[194:195] op_sel_hi:[1,0]
	v_pk_mul_f32 v[78:79], v[46:47], v[194:195] op_sel_hi:[1,0]
	v_pk_mul_f32 v[76:77], v[44:45], v[194:195] op_sel_hi:[1,0]
	v_pk_mul_f32 v[74:75], v[42:43], v[194:195] op_sel_hi:[1,0]
	v_pk_mul_f32 v[72:73], v[40:41], v[194:195] op_sel_hi:[1,0]
	v_pk_mul_f32 v[70:71], v[38:39], v[194:195] op_sel_hi:[1,0]
	v_pk_mul_f32 v[68:69], v[36:37], v[194:195] op_sel_hi:[1,0]
	v_pk_mul_f32 v[98:99], v[66:67], v[194:195] op_sel_hi:[1,0]
	v_pk_mul_f32 v[96:97], v[64:65], v[194:195] op_sel_hi:[1,0]
	v_pk_mul_f32 v[94:95], v[62:63], v[194:195] op_sel_hi:[1,0]
	v_pk_mul_f32 v[92:93], v[60:61], v[194:195] op_sel_hi:[1,0]
	v_pk_mul_f32 v[90:91], v[58:59], v[194:195] op_sel_hi:[1,0]
	v_pk_mul_f32 v[88:89], v[56:57], v[194:195] op_sel_hi:[1,0]
	v_pk_mul_f32 v[86:87], v[54:55], v[194:195] op_sel_hi:[1,0]
	v_pk_mul_f32 v[84:85], v[52:53], v[194:195] op_sel_hi:[1,0]
	v_cvt_pk_bf16_f32 v36, v149, v150
	v_cvt_pk_bf16_f32 v37, v151, v152
	v_cvt_pk_bf16_f32 v38, v153, v154
	v_cvt_pk_bf16_f32 v39, v155, v156
	s_nop 1
	v_mfma_f32_32x32x16_bf16 v[68:83], v[144:147], v[36:39], v[68:83]
	v_mfma_f32_32x32x16_bf16 v[84:99], v[140:143], v[36:39], v[84:99]
	v_cvt_pk_bf16_f32 v36, v157, v158
	v_cvt_pk_bf16_f32 v37, v159, v160
	v_cvt_pk_bf16_f32 v38, v161, v162
	v_cvt_pk_bf16_f32 v39, v163, v164
	s_nop 1
	v_mfma_f32_32x32x16_bf16 v[68:83], v[136:139], v[36:39], v[68:83]
	v_mfma_f32_32x32x16_bf16 v[84:99], v[132:135], v[36:39], v[84:99]
	v_mul_lo_u32 v36, s56, v222
	v_add_u32_e32 v40, s11, v36
	v_max_i32_e32 v164, 0, v40
	s_waitcnt vmcnt(0)
	v_lshl_add_u32 v38, v164, 7, v180
	s_mov_b32 m0, s57
	v_add_u32_e32 v40, s6, v40
	global_load_lds_dwordx4 v38, s[98:99]
	v_lshl_add_u32 v36, v164, 7, v182
	s_mov_b32 m0, s7
	v_max_i32_e32 v164, 0, v40
	global_load_lds_dwordx4 v36, s[100:101]
	v_readlane_b32 s7, v254, 28
	v_lshl_add_u32 v38, v164, 7, v180
	s_mov_b32 m0, s7
	v_readlane_b32 s7, v254, 29
	v_add_u32_e32 v40, s6, v40
	global_load_lds_dwordx4 v38, s[98:99]
	v_lshl_add_u32 v36, v164, 7, v182
	s_mov_b32 m0, s7
	v_max_i32_e32 v164, 0, v40
	global_load_lds_dwordx4 v36, s[100:101]
	v_lshl_add_u32 v38, v164, 7, v180
	s_mov_b32 m0, s15
	v_lshl_add_u32 v36, v164, 7, v182
	global_load_lds_dwordx4 v38, s[98:99]
	s_mov_b32 m0, s17
	v_sub_u32_e32 v52, v199, v223
	global_load_lds_dwordx4 v36, s[100:101]
	v_add_u32_e32 v36, s6, v40
	v_max_i32_e32 v164, 0, v36
	v_lshl_add_u32 v38, v164, 7, v180
	s_mov_b32 m0, s21
	v_readlane_b32 s6, v254, 30
	global_load_lds_dwordx4 v38, s[98:99]
	v_lshl_add_u32 v36, v164, 7, v182
	s_mov_b32 m0, s6
	v_mov_b32_e32 v53, v224
	global_load_lds_dwordx4 v36, s[100:101]
	ds_read_b128 v[160:163], v225
	ds_read_b128 v[156:159], v226
	ds_read_b128 v[152:155], v227
	ds_read_b128 v[148:151], v228
	s_waitcnt vmcnt(0)
	ds_read_b64_tr_b16 v[144:145], v229 offset:8192
	ds_read_b64_tr_b16 v[146:147], v229 offset:9216
	ds_read_b64_tr_b16 v[140:141], v229 offset:8256
	ds_read_b64_tr_b16 v[142:143], v229 offset:9280
	ds_read_b64_tr_b16 v[136:137], v229 offset:10240
	ds_read_b64_tr_b16 v[138:139], v229 offset:11264
	ds_read_b64_tr_b16 v[132:133], v229 offset:10304
	ds_read_b64_tr_b16 v[134:135], v229 offset:11328
	s_waitcnt lgkmcnt(0)
; __device__ __forceinline__ unsigned pk2(float lo, float hi) { return pg8::cvt_pk_bf16(lo, hi); }
; #define ATT_LOAD_Q(dst, J, set) do { const int qp_ = (J).pos0 + (32 * (set) + qc) * (J).d; _Pragma("unroll") for (int kk_ = 0; kk_ < 4; ++kk_) dst[kk_] = gld<bf16x8>(Qa + ((J).hb + (size_t)qp_) * 64 + 8 * h + 16 * kk_); } while (0)
; __device__ __forceinline__ void att_block(const bf16x8 (&kf)[4], const bf16x8 (&qf)[4], const bf16x8 (&va)[4], f32x16& o0, f32x16& o1, float& mrun, float& lrun, bool domask, int lo_, int hi_) {
;     ...
; #pragma unroll
;     for (int i = 0; i < 16; ++i) st[i] = 0.f;
; #pragma unroll
;     for (int kk = 0; kk < 4; ++kk) st = __builtin_amdgcn_mfma_f32_32x32x16_bf16(kf[kk], qf[kk], st, 0, 0, 0);
;     if (domask) {
;         asm volatile("" : "+v"(lo_), "+v"(hi_));
; #pragma unroll
;         for (int i = 0; i < 16; ++i) { const int ci = (i & 3) + 8 * (i >> 2); st[i] = ((ci - lo_) | (hi_ - ci)) < 0 ? -INFINITY : st[i]; }
;     }
;     float bmax = -INFINITY;
; #pragma unroll
;     for (int i = 0; i < 16; ++i) bmax = fmaxf(bmax, st[i]);
;     bmax = fmaxf(bmax, __shfl_xor(bmax, 32));
;     const float mnew = fmaxf(mrun, bmax);
;     float lsum = 0.f;
; #pragma unroll
;     for (int i = 0; i < 16; ++i) { st[i] = __builtin_amdgcn_exp2f(st[i] - mnew); lsum += st[i]; }
;     lsum += __shfl_xor(lsum, 32);
;     const float alpha = __builtin_amdgcn_exp2f(mrun - mnew);
;     lrun = lrun * alpha + lsum; mrun = mnew;
; #pragma unroll
;     for (int i = 0; i < 16; ++i) { o0[i] *= alpha; o1[i] *= alpha; }
; #pragma unroll
;     for (int s = 0; s < 2; ++s) { v4u w; w.x = pk2(st[8 * s], st[8 * s + 1]); w.y = pk2(st[8 * s + 2], st[8 * s + 3]); w.z = pk2(st[8 * s + 4], st[8 * s + 5]); w.w = pk2(st[8 * s + 6], st[8 * s + 7]);
;         const bf16x8 pb = __builtin_bit_cast(bf16x8, w);
;         o0 = __builtin_amdgcn_mfma_f32_32x32x16_bf16(va[2 * s], pb, o0, 0, 0, 0);
;         o1 = __builtin_amdgcn_mfma_f32_32x32x16_bf16(va[2 * s + 1], pb, o1, 0, 0, 0); }
; __device__ __forceinline__ void att_phase(unsigned char* ws, LAS unsigned char* lds, int lane, int wave, int G) {
;     ...
;                 att_block(kf, qfA, va, oA0, oA1, mA, lA, kb == 0 || kb == 4 || kminA > 32 * kb, mloA - 4 * h - 32 * kb, qc + 128 - 4 * h - 32 * kb);
;                 if (kb == 4 && hn) ATT_LOAD_Q(qfA, N, 0);
	v_mfma_f32_32x32x16_bf16 v[36:51], v[160:163], v[128:131], 0
	s_nop 0
	v_mfma_f32_32x32x16_bf16 v[36:51], v[156:159], v[124:127], v[36:51]
	v_mfma_f32_32x32x16_bf16 v[36:51], v[152:155], v[120:123], v[36:51]
	v_mfma_f32_32x32x16_bf16 v[36:51], v[148:151], v[116:119], v[36:51]
	s_nop 11
	s_mov_b32 vcc_lo, 0xffffffff
	s_mov_b32 vcc_hi, 0xfffffff0
	s_mov_b32 s24, 0xfffffffe
	s_mov_b32 s25, 0xffffffe0
	s_mov_b32 s26, 0xfffffffc
	s_mov_b32 s27, 0xffffffc0
	s_mov_b32 s28, 0xfffffff8
	s_mov_b32 s29, 0xffffff80
	v_cndmask_b32_e32 v36, v211, v36, vcc
	s_mov_b32 vcc_lo, 0xffffff00
	s_mov_b32 vcc_hi, 0xfffff000
	v_cndmask_b32_e64 v37, v211, v37, s[24:25]
	s_mov_b32 s24, 0xfffffe00
	s_mov_b32 s25, 0xffffe000
	v_cndmask_b32_e64 v38, v211, v38, s[26:27]
	s_mov_b32 s26, 0xfffffc00
	s_mov_b32 s27, 0xffffc000
	v_cndmask_b32_e64 v39, v211, v39, s[28:29]
	s_mov_b32 s28, 0xfffff800
	s_mov_b32 s29, 0xffff8000
	v_cndmask_b32_e32 v40, v211, v40, vcc
	s_mov_b32 vcc_lo, 0xffff0000
	s_mov_b32 vcc_hi, 0xfff00000
	v_cndmask_b32_e64 v41, v211, v41, s[24:25]
	s_mov_b32 s24, 0xfffe0000
	s_mov_b32 s25, 0xffe00000
	v_cndmask_b32_e64 v42, v211, v42, s[26:27]
	s_mov_b32 s26, 0xfffc0000
	s_mov_b32 s27, 0xffc00000
	v_cndmask_b32_e64 v43, v211, v43, s[28:29]
	s_mov_b32 s28, 0xfff80000
	s_mov_b32 s29, 0xff800000
	v_cndmask_b32_e32 v44, v211, v44, vcc
	s_mov_b32 vcc_lo, 0xff000000
	s_mov_b32 vcc_hi, 0xf0000000
	v_cndmask_b32_e64 v45, v211, v45, s[24:25]
	s_mov_b32 s24, 0xfe000000
	s_mov_b32 s25, 0xe0000000
	v_cndmask_b32_e64 v46, v211, v46, s[26:27]
	s_mov_b32 s26, 0xfc000000
	s_mov_b32 s27, 0xc0000000
	v_cndmask_b32_e64 v47, v211, v47, s[28:29]
	s_mov_b32 s28, 0xf8000000
	s_mov_b32 s29, 0x80000000
	v_cndmask_b32_e32 v48, v211, v48, vcc
	v_cndmask_b32_e64 v49, v211, v49, s[24:25]
	v_cndmask_b32_e64 v50, v211, v50, s[26:27]
	v_cndmask_b32_e64 v51, v211, v51, s[28:29]
	s_nop 0
	v_max3_f32 v52, v36, s58, v37
	v_max3_f32 v52, v52, v38, v39
	v_max3_f32 v52, v52, v40, v41
	v_max3_f32 v52, v52, v42, v43
	v_max3_f32 v52, v52, v44, v45
	v_max3_f32 v52, v52, v46, v47
	v_max3_f32 v52, v52, v48, v49
	v_max3_f32 v52, v52, v50, v51
	ds_bpermute_b32 v53, v201, v52
	s_andn2_b64 vcc, exec, s[2:3]
	s_waitcnt lgkmcnt(0)
	v_max3_f32 v200, v202, v52, v53
	v_sub_f32_e32 v36, v36, v200
	v_exp_f32_e32 v164, v36
	v_sub_f32_e32 v37, v37, v200
	v_exp_f32_e32 v166, v37
	v_sub_f32_e32 v37, v38, v200
	v_exp_f32_e32 v167, v37
	v_sub_f32_e32 v37, v39, v200
	v_exp_f32_e32 v199, v37
	v_sub_f32_e32 v37, v40, v200
	v_add_f32_e32 v36, 0, v164
	v_exp_f32_e32 v248, v37
	v_sub_f32_e32 v37, v41, v200
	v_add_f32_e32 v36, v166, v36
	v_exp_f32_e32 v249, v37
	v_sub_f32_e32 v37, v42, v200
	v_add_f32_e32 v36, v167, v36
	v_exp_f32_e32 v250, v37
	v_sub_f32_e32 v37, v43, v200
	v_add_f32_e32 v36, v199, v36
	v_exp_f32_e32 v251, v37
	v_sub_f32_e32 v37, v44, v200
	v_add_f32_e32 v36, v248, v36
	v_exp_f32_e32 v252, v37
	v_sub_f32_e32 v37, v45, v200
	v_add_f32_e32 v36, v249, v36
	v_exp_f32_e32 v203, v37
	v_sub_f32_e32 v37, v46, v200
	v_add_f32_e32 v36, v250, v36
	v_exp_f32_e32 v168, v37
	v_sub_f32_e32 v37, v47, v200
	v_add_f32_e32 v36, v251, v36
	v_exp_f32_e32 v169, v37
	v_sub_f32_e32 v37, v48, v200
	v_add_f32_e32 v36, v252, v36
	v_exp_f32_e32 v212, v37
	v_sub_f32_e32 v37, v49, v200
	v_add_f32_e32 v36, v203, v36
	v_exp_f32_e32 v209, v37
	v_sub_f32_e32 v37, v50, v200
	v_add_f32_e32 v36, v168, v36
	v_exp_f32_e32 v197, v37
	v_sub_f32_e32 v37, v51, v200
	v_add_f32_e32 v36, v169, v36
	v_exp_f32_e32 v195, v37
	v_add_f32_e32 v36, v212, v36
	v_add_f32_e32 v36, v209, v36
	v_add_f32_e32 v36, v197, v36
	v_add_f32_e32 v246, v195, v36
	v_sub_f32_e32 v36, v202, v200
	v_exp_f32_e32 v202, v36
	ds_bpermute_b32 v247, v201, v246
	v_pk_mul_f32 v[66:67], v[18:19], v[202:203] op_sel_hi:[1,0]
	v_pk_mul_f32 v[64:65], v[16:17], v[202:203] op_sel_hi:[1,0]
	v_pk_mul_f32 v[62:63], v[14:15], v[202:203] op_sel_hi:[1,0]
	v_pk_mul_f32 v[60:61], v[12:13], v[202:203] op_sel_hi:[1,0]
	v_pk_mul_f32 v[58:59], v[10:11], v[202:203] op_sel_hi:[1,0]
	v_pk_mul_f32 v[56:57], v[8:9], v[202:203] op_sel_hi:[1,0]
	v_pk_mul_f32 v[54:55], v[6:7], v[202:203] op_sel_hi:[1,0]
	v_pk_mul_f32 v[52:53], v[4:5], v[202:203] op_sel_hi:[1,0]
	v_pk_mul_f32 v[50:51], v[34:35], v[202:203] op_sel_hi:[1,0]
	v_pk_mul_f32 v[48:49], v[32:33], v[202:203] op_sel_hi:[1,0]
	v_pk_mul_f32 v[46:47], v[30:31], v[202:203] op_sel_hi:[1,0]
	v_pk_mul_f32 v[44:45], v[28:29], v[202:203] op_sel_hi:[1,0]
	v_pk_mul_f32 v[42:43], v[26:27], v[202:203] op_sel_hi:[1,0]
	v_pk_mul_f32 v[40:41], v[24:25], v[202:203] op_sel_hi:[1,0]
	v_pk_mul_f32 v[38:39], v[22:23], v[202:203] op_sel_hi:[1,0]
	v_pk_mul_f32 v[36:37], v[20:21], v[202:203] op_sel_hi:[1,0]
	v_cvt_pk_bf16_f32 v4, v164, v166
	v_cvt_pk_bf16_f32 v5, v167, v199
	v_cvt_pk_bf16_f32 v6, v248, v249
	v_cvt_pk_bf16_f32 v7, v250, v251
	s_nop 1
	v_mfma_f32_32x32x16_bf16 v[52:67], v[144:147], v[4:7], v[52:67]
	v_mfma_f32_32x32x16_bf16 v[36:51], v[140:143], v[4:7], v[36:51]
	v_cvt_pk_bf16_f32 v4, v252, v203
	v_cvt_pk_bf16_f32 v5, v168, v169
	v_cvt_pk_bf16_f32 v6, v212, v209
	v_cvt_pk_bf16_f32 v7, v197, v195
	s_nop 1
	v_mfma_f32_32x32x16_bf16 v[52:67], v[136:139], v[4:7], v[52:67]
	v_mfma_f32_32x32x16_bf16 v[36:51], v[132:135], v[4:7], v[36:51]
	v_cndmask_b32_e64 v4, 0, 1, s[2:3]
	v_cmp_ne_u32_e64 s[6:7], 1, v4
	s_cbranch_vccnz .LBB0_92
	v_ashrrev_i32_e32 v199, 31, v198
	v_lshl_add_u64 v[4:5], s[0:1], 0, v[198:199]
	v_lshlrev_b64 v[4:5], 7, v[4:5]
	v_lshl_add_u64 v[4:5], v[186:187], 0, v[4:5]
	global_load_dwordx4 v[128:131], v[4:5], off
	global_load_dwordx4 v[124:127], v[4:5], off offset:32
	global_load_dwordx4 v[120:123], v[4:5], off offset:64
	global_load_dwordx4 v[116:119], v[4:5], off offset:96

; __device__ __forceinline__ unsigned pk2(float lo, float hi) { return pg8::cvt_pk_bf16(lo, hi); }
; #define ATT_LOAD_Q(dst, J, set) do { const int qp_ = (J).pos0 + (32 * (set) + qc) * (J).d; _Pragma("unroll") for (int kk_ = 0; kk_ < 4; ++kk_) dst[kk_] = gld<bf16x8>(Qa + ((J).hb + (size_t)qp_) * 64 + 8 * h + 16 * kk_); } while (0)
; __device__ __forceinline__ void att_block(const bf16x8 (&kf)[4], const bf16x8 (&qf)[4], const bf16x8 (&va)[4], f32x16& o0, f32x16& o1, float& mrun, float& lrun, bool domask, int lo_, int hi_) {
;     ...
; #pragma unroll
;     for (int i = 0; i < 16; ++i) st[i] = 0.f;
; #pragma unroll
;     for (int kk = 0; kk < 4; ++kk) st = __builtin_amdgcn_mfma_f32_32x32x16_bf16(kf[kk], qf[kk], st, 0, 0, 0);
;     if (domask) {
;         asm volatile("" : "+v"(lo_), "+v"(hi_));
; #pragma unroll
;         for (int i = 0; i < 16; ++i) { const int ci = (i & 3) + 8 * (i >> 2); st[i] = ((ci - lo_) | (hi_ - ci)) < 0 ? -INFINITY : st[i]; }
;     }
;     float bmax = -INFINITY;
; #pragma unroll
;     for (int i = 0; i < 16; ++i) bmax = fmaxf(bmax, st[i]);
;     bmax = fmaxf(bmax, __shfl_xor(bmax, 32));
;     const float mnew = fmaxf(mrun, bmax);
;     float lsum = 0.f;
; #pragma unroll
;     for (int i = 0; i < 16; ++i) { st[i] = __builtin_amdgcn_exp2f(st[i] - mnew); lsum += st[i]; }
;     lsum += __shfl_xor(lsum, 32);
;     const float alpha = __builtin_amdgcn_exp2f(mrun - mnew);
;     lrun = lrun * alpha + lsum; mrun = mnew;
; #pragma unroll
;     for (int i = 0; i < 16; ++i) { o0[i] *= alpha; o1[i] *= alpha; }
; #pragma unroll
;     for (int s = 0; s < 2; ++s) { v4u w; w.x = pk2(st[8 * s], st[8 * s + 1]); w.y = pk2(st[8 * s + 2], st[8 * s + 3]); w.z = pk2(st[8 * s + 4], st[8 * s + 5]); w.w = pk2(st[8 * s + 6], st[8 * s + 7]);
;         const bf16x8 pb = __builtin_bit_cast(bf16x8, w);
;         o0 = __builtin_amdgcn_mfma_f32_32x32x16_bf16(va[2 * s], pb, o0, 0, 0, 0);
;         o1 = __builtin_amdgcn_mfma_f32_32x32x16_bf16(va[2 * s + 1], pb, o1, 0, 0, 0); }
; __device__ __forceinline__ void att_phase(unsigned char* ws, LAS unsigned char* lds, int lane, int wave, int G) {
;     ...
;                 att_block(kf, qfB, va, oB0, oB1, mB, lB, kb == 1 || kb == 5 || kminB > 32 * (kb - 1), mloB - 4 * h - 32 * (kb - 1), qc + 128 - 4 * h - 32 * (kb - 1));
;                 if (kb == 5 && hn) ATT_LOAD_Q(qfB, N, 1);
.LBB0_96:
	ds_read_b128 v[68:71], v225 offset:4096
	ds_read_b128 v[132:135], v226 offset:4096
	ds_read_b128 v[136:139], v227 offset:4096
	ds_read_b128 v[140:143], v228 offset:4096
	s_waitcnt vmcnt(0)
	ds_read_b64_tr_b16 v[92:93], v229 offset:12288
	ds_read_b64_tr_b16 v[94:95], v229 offset:13312
	ds_read_b64_tr_b16 v[86:87], v229 offset:13376
	ds_read_b64_tr_b16 v[84:85], v229 offset:12352
	s_waitcnt lgkmcnt(0)
	v_mfma_f32_32x32x16_bf16 v[68:83], v[68:71], v[112:115], 0
	v_sub_u32_e32 v144, v237, v223
	v_mov_b32_e32 v145, v224
	ds_read_b64_tr_b16 v[96:97], v229 offset:14336
	ds_read_b64_tr_b16 v[98:99], v229 offset:15360
	ds_read_b64_tr_b16 v[90:91], v229 offset:15424
	ds_read_b64_tr_b16 v[88:89], v229 offset:14400
	s_mov_b32 s14, 0xff800000
	v_mfma_f32_32x32x16_bf16 v[68:83], v[132:135], v[108:111], v[68:83]
	v_mfma_f32_32x32x16_bf16 v[68:83], v[136:139], v[104:107], v[68:83]
	v_mfma_f32_32x32x16_bf16 v[68:83], v[140:143], v[100:103], v[68:83]
	s_nop 11
	s_mov_b32 vcc_lo, 0xffffffff
	s_mov_b32 vcc_hi, 0xfffffff0
	s_mov_b32 s24, 0xfffffffe
	s_mov_b32 s25, 0xffffffe0
	s_mov_b32 s26, 0xfffffffc
	s_mov_b32 s27, 0xffffffc0
	s_mov_b32 s28, 0xfffffff8
	s_mov_b32 s29, 0xffffff80
	v_cndmask_b32_e32 v68, v211, v68, vcc
	s_mov_b32 vcc_lo, 0xffffff00
	s_mov_b32 vcc_hi, 0xfffff000
	v_cndmask_b32_e64 v69, v211, v69, s[24:25]
	s_mov_b32 s24, 0xfffffe00
	s_mov_b32 s25, 0xffffe000
	v_cndmask_b32_e64 v70, v211, v70, s[26:27]
	s_mov_b32 s26, 0xfffffc00
	s_mov_b32 s27, 0xffffc000
	v_cndmask_b32_e64 v71, v211, v71, s[28:29]
	s_mov_b32 s28, 0xfffff800
	s_mov_b32 s29, 0xffff8000
	v_cndmask_b32_e32 v72, v211, v72, vcc
	s_mov_b32 vcc_lo, 0xffff0000
	s_mov_b32 vcc_hi, 0xfff00000
	v_cndmask_b32_e64 v73, v211, v73, s[24:25]
	s_mov_b32 s24, 0xfffe0000
	s_mov_b32 s25, 0xffe00000
	v_cndmask_b32_e64 v74, v211, v74, s[26:27]
	s_mov_b32 s26, 0xfffc0000
	s_mov_b32 s27, 0xffc00000
	v_cndmask_b32_e64 v75, v211, v75, s[28:29]
	s_mov_b32 s28, 0xfff80000
	s_mov_b32 s29, 0xff800000
	v_cndmask_b32_e32 v132, v211, v76, vcc
	s_mov_b32 vcc_lo, 0xff000000
	s_mov_b32 vcc_hi, 0xf0000000
	v_cndmask_b32_e64 v77, v211, v77, s[24:25]
	s_mov_b32 s24, 0xfe000000
	s_mov_b32 s25, 0xe0000000
	v_cndmask_b32_e64 v78, v211, v78, s[26:27]
	s_mov_b32 s26, 0xfc000000
	s_mov_b32 s27, 0xc0000000
	v_cndmask_b32_e64 v79, v211, v79, s[28:29]
	s_mov_b32 s28, 0xf8000000
	s_mov_b32 s29, 0x80000000
	v_cndmask_b32_e32 v80, v211, v80, vcc
	v_cndmask_b32_e64 v81, v211, v81, s[24:25]
	v_cndmask_b32_e64 v82, v211, v82, s[26:27]
	v_cndmask_b32_e64 v83, v211, v83, s[28:29]
	s_nop 0
	s_nop 1
	s_nop 1
	s_nop 0
	v_max3_f32 v76, v68, s14, v69
	v_max3_f32 v76, v76, v70, v71
	v_max3_f32 v76, v76, v72, v73
	v_max3_f32 v76, v76, v74, v75
	v_max3_f32 v76, v76, v132, v77
	v_max3_f32 v76, v76, v78, v79
	v_max3_f32 v76, v76, v80, v81
	v_max3_f32 v76, v76, v82, v83
	ds_bpermute_b32 v133, v201, v76
	s_and_b64 vcc, exec, s[6:7]
	s_waitcnt lgkmcnt(0)
	v_max3_f32 v76, v151, v76, v133
	v_sub_f32_e32 v68, v68, v76
	v_exp_f32_e32 v68, v68
	v_sub_f32_e32 v69, v69, v76
	v_exp_f32_e32 v69, v69
	v_sub_f32_e32 v70, v70, v76
	v_exp_f32_e32 v70, v70
	v_sub_f32_e32 v71, v71, v76
	v_exp_f32_e32 v71, v71
	v_sub_f32_e32 v72, v72, v76
	v_add_f32_e32 v133, 0, v68
	v_exp_f32_e32 v72, v72
	v_sub_f32_e32 v73, v73, v76
	v_add_f32_e32 v133, v69, v133
	v_exp_f32_e32 v73, v73
	v_sub_f32_e32 v74, v74, v76
	v_add_f32_e32 v133, v70, v133
	v_exp_f32_e32 v74, v74
	v_sub_f32_e32 v75, v75, v76
	v_add_f32_e32 v133, v71, v133
	v_exp_f32_e32 v75, v75
	v_sub_f32_e32 v132, v132, v76
	v_add_f32_e32 v133, v72, v133
	v_exp_f32_e32 v132, v132
	v_sub_f32_e32 v77, v77, v76
	v_add_f32_e32 v133, v73, v133
	v_exp_f32_e32 v77, v77
	v_sub_f32_e32 v78, v78, v76
	v_add_f32_e32 v133, v74, v133
	v_exp_f32_e32 v134, v78
	v_add_f32_e32 v78, v75, v133
	v_add_f32_e32 v78, v132, v78
	v_add_f32_e32 v78, v77, v78
	v_add_f32_e32 v133, v134, v78
	v_sub_f32_e32 v78, v79, v76
	v_exp_f32_e32 v79, v78
	v_sub_f32_e32 v78, v80, v76
	v_exp_f32_e32 v80, v78
	v_sub_f32_e32 v78, v151, v76
	v_exp_f32_e32 v78, v78
	v_cvt_pk_bf16_f32 v68, v68, v69
	v_cvt_pk_bf16_f32 v69, v70, v71
	v_cvt_pk_bf16_f32 v70, v72, v73
	v_pk_mul_f32 v[34:35], v[34:35], v[78:79] op_sel_hi:[1,0]
	v_pk_mul_f32 v[32:33], v[32:33], v[78:79] op_sel_hi:[1,0]
	v_pk_mul_f32 v[30:31], v[30:31], v[78:79] op_sel_hi:[1,0]
	v_pk_mul_f32 v[28:29], v[28:29], v[78:79] op_sel_hi:[1,0]
	v_pk_mul_f32 v[26:27], v[26:27], v[78:79] op_sel_hi:[1,0]
	v_pk_mul_f32 v[24:25], v[24:25], v[78:79] op_sel_hi:[1,0]
	v_pk_mul_f32 v[22:23], v[22:23], v[78:79] op_sel_hi:[1,0]
	v_pk_mul_f32 v[20:21], v[20:21], v[78:79] op_sel_hi:[1,0]
	v_pk_mul_f32 v[18:19], v[18:19], v[78:79] op_sel_hi:[1,0]
	v_cvt_pk_bf16_f32 v71, v74, v75
	v_pk_mul_f32 v[16:17], v[16:17], v[78:79] op_sel_hi:[1,0]
	v_pk_mul_f32 v[14:15], v[14:15], v[78:79] op_sel_hi:[1,0]
	v_pk_mul_f32 v[12:13], v[12:13], v[78:79] op_sel_hi:[1,0]
	v_pk_mul_f32 v[10:11], v[10:11], v[78:79] op_sel_hi:[1,0]
	v_pk_mul_f32 v[8:9], v[8:9], v[78:79] op_sel_hi:[1,0]
	v_pk_mul_f32 v[6:7], v[6:7], v[78:79] op_sel_hi:[1,0]
	v_pk_mul_f32 v[4:5], v[4:5], v[78:79] op_sel_hi:[1,0]
	v_mfma_f32_32x32x16_bf16 v[20:35], v[92:95], v[68:71], v[20:35]
	v_sub_f32_e32 v81, v81, v76
	v_sub_f32_e32 v82, v82, v76
	v_exp_f32_e32 v81, v81
	v_exp_f32_e32 v72, v82
	v_add_f32_e32 v74, v79, v133
	v_add_f32_e32 v74, v80, v74
	v_add_f32_e32 v74, v81, v74
	v_mfma_f32_32x32x16_bf16 v[4:19], v[84:87], v[68:71], v[4:19]
	v_sub_f32_e32 v68, v83, v76
	v_exp_f32_e32 v73, v68
	v_cvt_pk_bf16_f32 v68, v132, v77
	v_cvt_pk_bf16_f32 v69, v134, v79
	v_cvt_pk_bf16_f32 v70, v80, v81
	v_cvt_pk_bf16_f32 v71, v72, v73
	v_add_f32_e32 v72, v72, v74
	v_add_f32_e32 v77, v73, v72
	v_mfma_f32_32x32x16_bf16 v[20:35], v[96:99], v[68:71], v[20:35]
	ds_bpermute_b32 v79, v201, v77
	v_mfma_f32_32x32x16_bf16 v[4:19], v[88:91], v[68:71], v[4:19]
	s_cbranch_vccnz .LBB0_98
	v_lshl_add_u32 v68, s52, 5, v198
	v_ashrrev_i32_e32 v69, 31, v68
	v_lshl_add_u64 v[68:69], s[0:1], 0, v[68:69]
	v_lshlrev_b64 v[68:69], 7, v[68:69]
	v_lshl_add_u64 v[68:69], v[186:187], 0, v[68:69]
	global_load_dwordx4 v[112:115], v[68:69], off
	global_load_dwordx4 v[108:111], v[68:69], off offset:32
	global_load_dwordx4 v[104:107], v[68:69], off offset:64
	global_load_dwordx4 v[100:103], v[68:69], off offset:96
